# GEMM1 K-loop re-cut to 4 phases of 32 MFMAs (half the barriers, balanced DMA per load segment); P5/P6 loops keep the setprio-before-barrier edit
# speedup vs baseline: 1.0421x; 1.0077x over previous
; #define PG8_STAGE(bufoff, gbase, voff) do { _Pragma("unroll") for (int _i = 0; _i < 2; ++_i) \
;         __builtin_amdgcn_global_load_lds((const unsigned*)((const char*)(gbase) + (voff)[_i]), (LAS unsigned*)(lds + (bufoff) + ldsw + _i * 8192), 16, 0, 0); } while (0)
; #define PG8_WAIT_V(n) asm volatile("s_waitcnt vmcnt(" #n ")" ::: "memory")
; #define PG8_BAR __builtin_amdgcn_s_barrier()
; template <class Epi>
; DI void gemm_phase(LAS unsigned char* lds, const Gemm g, const StaticOrder& S_, const Epi& E) {
;     ...
;     const char* cA0 = (const char*)g.A0 + (size_t)cur.pm * tstepA; const char* cA1 = (const char*)g.A1 + (size_t)cur.pm * tstepA;
;     const char* cB0 = (const char*)g.B0 + (size_t)cur.pn * tstepB; const char* cB1 = (const char*)g.B1 + (size_t)cur.pn * tstepB;
;     PG8_STAGE(PG8_SB(0, 0), cB0, voffB); PG8_STAGE(PG8_SA(0, 0), cA0, voffA); PG8_STAGE(PG8_SB(0, 1), cB0 + hstepB, voffB); PG8_STAGE(PG8_SA(0, 1), cA0 + hstepA, voffA);
;     if (wr == 1) PG8_BAR;
;     PG8_WAIT_V(4); PG8_BAR;
;     PG8_STAGE(PG8_SB(1, 0), cB0 + kstep, voffB); PG8_STAGE(PG8_SA(1, 0), cA0 + kstep, voffA); PG8_STAGE(PG8_SB(1, 1), cB0 + hstepB + kstep, voffB);
;     PG8_WAIT_V(6); PG8_BAR;
.LBB0_109:
	s_mov_b64 s[22:23], 0x80
	s_and_b32 s18, s18, 3
	s_add_i32 m0, s69, 0x18000
	v_lshl_add_u64 v[6:7], v[6:7], 0, s[22:23]
	s_lshl_b32 s21, s5, 13
	s_lshl_b32 s20, s18, 5
	s_lshl_b32 s34, s18, 12
	s_waitcnt vmcnt(0)
	s_barrier
	global_load_lds_dwordx4 v[6:7], off
	v_lshl_add_u64 v[4:5], v[4:5], 0, s[22:23]
	s_add_i32 m0, s69, 0x1a000
	s_add_i32 s74, s69, 0x8000
	s_add_i32 s75, s69, 0xa000
	global_load_lds_dwordx4 v[4:5], off
	v_lshl_add_u64 v[2:3], v[2:3], 0, s[22:23]
	s_mov_b32 m0, s74
	s_add_u32 s30, s48, 0x80080
	global_load_lds_dwordx4 v[2:3], off
	v_lshl_add_u64 v[0:1], v[0:1], 0, s[22:23]
	s_mov_b32 m0, s75
	s_addc_u32 s31, s49, 0
	global_load_lds_dwordx4 v[0:1], off
	s_add_i32 m0, s69, 0x1c000
	v_lshl_add_u64 v[0:1], s[30:31], 0, v[180:181]
	global_load_lds_dwordx4 v[0:1], off
	v_lshl_add_u64 v[0:1], s[30:31], 0, v[176:177]
	v_mov_b64_e32 v[250:251], v[0:1]
	s_add_i32 m0, s69, 0x1e000
	s_add_u32 s78, s10, 0x12000000
	global_load_lds_dwordx4 v[0:1], off
	v_and_b32_e32 v1, 3, v204
	v_and_b32_e32 v0, 15, v202
	v_lshlrev_b32_e32 v184, 4, v1
	v_lshl_or_b32 v207, s5, 6, v0
	v_lshlrev_b32_e32 v186, 3, v1
	v_lshl_or_b32 v0, v0, 6, v184
	v_and_b32_e32 v1, 32, v206
	s_sext_i32_i16 s50, s4
	v_bitop3_b32 v2, v0, s21, v1 bitop3:0xde
	v_lshlrev_b32_e32 v0, 6, v202
	s_movk_i32 s4, 0x3c0
	s_addc_u32 s79, s11, 0
	v_and_or_b32 v0, v0, s4, v184
	s_add_u32 s30, s10, 0xe000000
	v_bitop3_b32 v208, s34, v0, v1 bitop3:0xf6
	s_addc_u32 s31, s11, 0
	v_lshl_add_u64 v[0:1], s[10:11], 0, v[184:185]
	s_mov_b64 s[38:39], 0x1b800000
	s_add_u32 s34, s10, 0x8000000
	v_lshl_add_u64 v[188:189], v[0:1], 0, s[38:39]
	v_lshlrev_b32_e32 v0, 9, v202
	s_addc_u32 s35, s11, 0
	v_and_b32_e32 v0, 0x70000, v0
	v_lshlrev_b32_e32 v1, 12, v11
	s_add_u32 s36, s10, 0x4000000
	v_or3_b32 v0, v9, v0, v1
	s_addc_u32 s37, s11, 0
	v_add_u32_e32 v190, v0, v10
	v_lshlrev_b32_e32 v0, 5, v8
	s_waitcnt vmcnt(6)
	s_cmp_eq_u32 s18, 0
	v_and_b32_e32 v0, 0xf0000, v0
	s_cselect_b64 s[4:5], -1, 0
	v_or3_b32 v0, v9, v0, v1
	s_add_i32 s82, 0, 0x10000
	s_add_i32 s83, 0, 0x14000
	s_mov_b32 s76, 0x8000
	s_mov_b32 s77, 0xa000
	v_or_b32_e32 v209, s20, v186
	s_mov_b32 s21, s19
	v_mov_b32_e32 v187, v185
	s_ashr_i32 s80, s24, 31
	s_mov_b32 s81, s24
	v_mov_b32_e32 v191, v185
	v_add_u32_e32 v192, v0, v10
	v_mov_b32_e32 v193, v185
	v_mov_b64_e32 v[194:195], 0xd00
	v_mov_b64_e32 v[196:197], 0xcff
	v_add_u32_e32 v210, s82, v208
	v_add_u32_e32 v211, 0, v2
	v_add_u32_e32 v212, s83, v208
	s_mov_b32 s84, 0x437f0000
	s_movk_i32 s85, 0x1000
	s_movk_i32 s86, 0x3000
	s_mov_b32 s87, 0x9000
	s_mov_b32 s88, 0xb000
	s_mov_b32 s89, 0x102000
	s_xor_b64 s[38:39], s[4:5], -1
	s_mov_b32 s90, 0
	s_barrier
	s_branch .LBB0_111

; #define PG8_STAGE(bufoff, gbase, voff) do { _Pragma("unroll") for (int _i = 0; _i < 2; ++_i) \
;         __builtin_amdgcn_global_load_lds((const unsigned*)((const char*)(gbase) + (voff)[_i]), (LAS unsigned*)(lds + (bufoff) + ldsw + _i * 8192), 16, 0, 0); } while (0)
; #define PG8_LDA(dst, b, h) do { _Pragma("unroll") for (int m = 0; m < 4; ++m) _Pragma("unroll") for (int k = 0; k < 2; ++k) dst[m][k] = *(const LAS bf16x8*)(lds + PG8_SA(b, h) + aoff + m * 2048 + k * 1024); } while (0)
; #define PG8_LDB(dst, b, h) do { _Pragma("unroll") for (int n = 0; n < 2; ++n) _Pragma("unroll") for (int k = 0; k < 2; ++k) dst[n][k] = *(const LAS bf16x8*)(lds + PG8_SB(b, h) + boff + n * 2048 + k * 1024); } while (0)
; #define PG8_MMA(ai, bj, At, Bt) do { __builtin_amdgcn_s_setprio(1); _Pragma("unroll") for (int m = 0; m < 4; ++m) _Pragma("unroll") for (int n = 0; n < 2; ++n) _Pragma("unroll") for (int k = 0; k < 2; ++k) \
;         acc[ai][bj][m][n] = __builtin_amdgcn_mfma_f32_16x16x32_bf16(Bt[n][k], At[m][k], acc[ai][bj][m][n], 0, 0, 0); __builtin_amdgcn_s_setprio(0); } while (0)
; #define PG8_WAIT_L(n) asm volatile("s_waitcnt lgkmcnt(" #n ")" ::: "memory")
; #define PG8_BAR __builtin_amdgcn_s_barrier()
; #define PG8_SCHED __builtin_amdgcn_sched_barrier(0)
; template <class Epi>
; DI void gemm_phase(LAS unsigned char* lds, const Gemm g, const StaticOrder& S_, const Epi& E) {
;     ...
;         for (int t = tb; t < te; t += 2) {
;             const bool last = (t == nt - 2);
;             const bool hA = (t >= ksplit), hB = (t + 2 >= ksplit);
;             const char* a1 = (hA ? cA1 : cA0) + (size_t)(t + 1) * kstep;
;             const char* a2 = last ? nA0 : (hB ? cA1 : cA0) + (size_t)(t + 2) * kstep; const char* b2 = last ? nB0 : (hB ? cB1 : cB0) + (size_t)(t + 2) * kstep;
;             const char* a3 = a2 + kstep; const char* b3 = b2 + kstep;
;             PG8_LDB(B0, 0, 0); PG8_SCHED; PG8_LDA(At, 0, 0); PG8_STAGE(PG8_SA(1, 1), a1 + hstepA, voffA);
;             PG8_WAIT_L(8); PG8_BAR; PG8_WAIT_L(0); PG8_MMA(0, 0, At, B0); PG8_BAR; PG8_SCHED;
;             PG8_LDB(B1, 0, 1); PG8_STAGE(PG8_SB(0, 0), b2, voffB);
;             PG8_BAR; PG8_WAIT_L(0); PG8_MMA(0, 1, At, B1); PG8_BAR;
;             PG8_LDA(At, 0, 1); PG8_STAGE(PG8_SA(0, 0), a2, voffA);
;             PG8_BAR; PG8_WAIT_L(0); PG8_MMA(1, 0, At, B0); PG8_BAR; PG8_SCHED;
.LBB0_114:
	s_add_i32 s94, s56, 2
	s_cmp_gt_u32 s94, 29
	s_cselect_b64 s[58:59], -1, 0
	s_and_b64 vcc, s[58:59], exec
	s_cselect_b32 s58, s18, s6
	s_cselect_b32 s57, s51, s7
	s_cselect_b32 s59, s91, s49
	s_cselect_b32 s95, s53, s48
	s_add_u32 s58, s58, s54
	s_addc_u32 s57, s57, s55
	s_add_u32 s58, s58, 0xfff80080
	s_addc_u32 s57, s57, -1
	s_add_u32 s95, s95, s54
	s_addc_u32 s59, s59, s55
	s_add_u32 s95, s95, 0xfff80080
	s_addc_u32 s96, s59, -1
	s_cmp_eq_u32 s56, 28
	s_cselect_b32 s56, s93, s95
	s_cselect_b32 s59, s43, s57
	s_cselect_b32 s58, s92, s58
	s_cselect_b32 s57, s41, s96
	ds_read_b128 v[132:135], v210
	ds_read_b128 v[136:139], v210 offset:1024
	ds_read_b128 v[140:143], v210 offset:2048
	ds_read_b128 v[144:147], v210 offset:3072
	ds_read_b128 v[214:217], v212
	ds_read_b128 v[218:221], v212 offset:1024
	ds_read_b128 v[222:225], v212 offset:2048
	ds_read_b128 v[226:229], v212 offset:3072
	s_sub_u32 s96, s54, 0x80000
	s_subb_u32 s97, s55, 0
	ds_read_b128 v[148:151], v211
	ds_read_b128 v[152:155], v211 offset:1024
	ds_read_b128 v[156:159], v211 offset:2048
	ds_read_b128 v[160:163], v211 offset:3072
	ds_read_b128 v[164:167], v211 offset:4096
	ds_read_b128 v[168:171], v211 offset:5120
	ds_read_b128 v[172:175], v211 offset:6144
	ds_read_b128 v[198:201], v211 offset:7168
	s_mov_b32 m0, s74
	v_lshl_add_u64 v[238:239], v[128:129], 0, s[96:97]
	global_load_lds_dwordx4 v[238:239], off
	s_mov_b32 m0, s75
	v_lshl_add_u64 v[238:239], v[130:131], 0, s[96:97]
	global_load_lds_dwordx4 v[238:239], off
	s_add_i32 m0, s64, 0x1e000
	s_nop 0
	global_load_lds_dwordx4 v[250:251], off
	s_waitcnt vmcnt(3)
	s_waitcnt lgkmcnt(8)
	s_setprio 1
	s_barrier
	s_waitcnt lgkmcnt(0)
	v_mfma_f32_16x16x32_bf16 v[124:127], v[132:135], v[148:151], v[124:127]
	v_mfma_f32_16x16x32_bf16 v[120:123], v[140:143], v[148:151], v[120:123]
	v_mfma_f32_16x16x32_bf16 v[108:111], v[132:135], v[156:159], v[108:111]
	v_mfma_f32_16x16x32_bf16 v[104:107], v[140:143], v[156:159], v[104:107]
	v_mfma_f32_16x16x32_bf16 v[92:95], v[132:135], v[164:167], v[92:95]
	v_mfma_f32_16x16x32_bf16 v[88:91], v[140:143], v[164:167], v[88:91]
	v_mfma_f32_16x16x32_bf16 v[76:79], v[132:135], v[172:175], v[76:79]
	v_mfma_f32_16x16x32_bf16 v[72:75], v[140:143], v[172:175], v[72:75]
	v_mfma_f32_16x16x32_bf16 v[124:127], v[136:139], v[152:155], v[124:127]
	v_mfma_f32_16x16x32_bf16 v[120:123], v[144:147], v[152:155], v[120:123]
	v_mfma_f32_16x16x32_bf16 v[108:111], v[136:139], v[160:163], v[108:111]
	v_mfma_f32_16x16x32_bf16 v[104:107], v[144:147], v[160:163], v[104:107]
	v_mfma_f32_16x16x32_bf16 v[92:95], v[136:139], v[168:171], v[92:95]
	v_mfma_f32_16x16x32_bf16 v[88:91], v[144:147], v[168:171], v[88:91]
	v_mfma_f32_16x16x32_bf16 v[76:79], v[136:139], v[198:201], v[76:79]
	v_mfma_f32_16x16x32_bf16 v[72:75], v[144:147], v[198:201], v[72:75]
	v_mfma_f32_16x16x32_bf16 v[116:119], v[214:217], v[148:151], v[116:119]
	v_mfma_f32_16x16x32_bf16 v[112:115], v[222:225], v[148:151], v[112:115]
	v_mfma_f32_16x16x32_bf16 v[100:103], v[214:217], v[156:159], v[100:103]
	v_mfma_f32_16x16x32_bf16 v[96:99], v[222:225], v[156:159], v[96:99]
	v_mfma_f32_16x16x32_bf16 v[84:87], v[214:217], v[164:167], v[84:87]
	v_mfma_f32_16x16x32_bf16 v[80:83], v[222:225], v[164:167], v[80:83]
	v_mfma_f32_16x16x32_bf16 v[68:71], v[214:217], v[172:175], v[68:71]
	v_mfma_f32_16x16x32_bf16 v[64:67], v[222:225], v[172:175], v[64:67]
	v_mfma_f32_16x16x32_bf16 v[116:119], v[218:221], v[152:155], v[116:119]
	v_mfma_f32_16x16x32_bf16 v[112:115], v[226:229], v[152:155], v[112:115]
	v_mfma_f32_16x16x32_bf16 v[100:103], v[218:221], v[160:163], v[100:103]
	v_mfma_f32_16x16x32_bf16 v[96:99], v[226:229], v[160:163], v[96:99]
	v_mfma_f32_16x16x32_bf16 v[84:87], v[218:221], v[168:171], v[84:87]
	v_mfma_f32_16x16x32_bf16 v[80:83], v[226:229], v[168:171], v[80:83]
	v_mfma_f32_16x16x32_bf16 v[68:71], v[218:221], v[198:201], v[68:71]
	v_mfma_f32_16x16x32_bf16 v[64:67], v[226:229], v[198:201], v[64:67]
	s_setprio 0
	s_barrier
	ds_read_b128 v[148:151], v211 offset:16384
	ds_read_b128 v[152:155], v211 offset:17408
	ds_read_b128 v[156:159], v211 offset:18432
	ds_read_b128 v[160:163], v211 offset:19456
	ds_read_b128 v[164:167], v211 offset:20480
	ds_read_b128 v[168:171], v211 offset:21504
	ds_read_b128 v[172:175], v211 offset:22528
	ds_read_b128 v[198:201], v211 offset:23552
	s_add_i32 m0, s64, 0x10000
	v_lshl_add_u64 v[230:231], s[56:57], 0, v[180:181]
	global_load_lds_dwordx4 v[230:231], off
	s_add_i32 m0, s64, 0x12000
	v_lshl_add_u64 v[232:233], s[56:57], 0, v[176:177]
	global_load_lds_dwordx4 v[232:233], off
	s_add_u32 s96, s56, 0x80000
	s_addc_u32 s97, s57, 0
	s_add_i32 m0, s64, 0x14000
	v_lshl_add_u64 v[238:239], s[96:97], 0, v[180:181]
	global_load_lds_dwordx4 v[238:239], off
	v_lshl_add_u64 v[242:243], s[96:97], 0, v[176:177]
	s_add_i32 m0, s69, 0xc000
	v_lshl_add_u64 v[240:241], v[128:129], 0, s[54:55]
	global_load_lds_dwordx4 v[240:241], off
	s_add_i32 m0, s69, 0xe000
	v_lshl_add_u64 v[240:241], v[130:131], 0, s[54:55]
	global_load_lds_dwordx4 v[240:241], off
	v_lshl_add_u64 v[234:235], s[58:59], 0, v[182:183]
	s_waitcnt vmcnt(5)
	s_setprio 1
	s_barrier
; #define PG8_STAGE(bufoff, gbase, voff) do { _Pragma("unroll") for (int _i = 0; _i < 2; ++_i) \
;         __builtin_amdgcn_global_load_lds((const unsigned*)((const char*)(gbase) + (voff)[_i]), (LAS unsigned*)(lds + (bufoff) + ldsw + _i * 8192), 16, 0, 0); } while (0)
; #define PG8_LDA(dst, b, h) do { _Pragma("unroll") for (int m = 0; m < 4; ++m) _Pragma("unroll") for (int k = 0; k < 2; ++k) dst[m][k] = *(const LAS bf16x8*)(lds + PG8_SA(b, h) + aoff + m * 2048 + k * 1024); } while (0)
; #define PG8_LDB(dst, b, h) do { _Pragma("unroll") for (int n = 0; n < 2; ++n) _Pragma("unroll") for (int k = 0; k < 2; ++k) dst[n][k] = *(const LAS bf16x8*)(lds + PG8_SB(b, h) + boff + n * 2048 + k * 1024); } while (0)
; #define PG8_WAIT_V(n) asm volatile("s_waitcnt vmcnt(" #n ")" ::: "memory")
; #define PG8_WAIT_L(n) asm volatile("s_waitcnt lgkmcnt(" #n ")" ::: "memory")
; #define PG8_BAR __builtin_amdgcn_s_barrier()
; #define PG8_SCHED __builtin_amdgcn_sched_barrier(0)
; template <class Epi>
; DI void gemm_phase(LAS unsigned char* lds, const Gemm g, const StaticOrder& S_, const Epi& E) {
;     ...
;             PG8_LDB(B0, 0, 0); PG8_SCHED; PG8_LDA(At, 0, 0); PG8_STAGE(PG8_SA(1, 1), a1 + hstepA, voffA);
;             PG8_WAIT_L(8); PG8_BAR; PG8_WAIT_L(0); PG8_MMA(0, 0, At, B0); PG8_BAR; PG8_SCHED;
;             PG8_LDB(B1, 0, 1); PG8_STAGE(PG8_SB(0, 0), b2, voffB);
;             PG8_BAR; PG8_WAIT_L(0); PG8_MMA(0, 1, At, B1); PG8_BAR;
;             PG8_LDA(At, 0, 1); PG8_STAGE(PG8_SA(0, 0), a2, voffA);
;             PG8_BAR; PG8_WAIT_L(0); PG8_MMA(1, 0, At, B0); PG8_BAR; PG8_SCHED;
;             PG8_STAGE(PG8_SB(0, 1), b2 + hstepB, voffB);
;             PG8_WAIT_V(6); PG8_BAR; PG8_MMA(1, 1, At, B1); PG8_BAR;
;             PG8_LDB(B0, 1, 0); PG8_SCHED; PG8_LDA(At, 1, 0); PG8_STAGE(PG8_SA(0, 1), a2 + hstepA, voffA);
;             PG8_WAIT_L(8); PG8_BAR; PG8_WAIT_L(0); PG8_MMA(0, 0, At, B0); PG8_BAR; PG8_SCHED;
;             PG8_LDB(B1, 1, 1); PG8_STAGE(PG8_SB(1, 0), b3, voffB);
;             PG8_BAR; PG8_WAIT_L(0); PG8_MMA(0, 1, At, B1); PG8_BAR;
;             PG8_LDA(At, 1, 1); PG8_STAGE(PG8_SA(1, 0), a3, voffA);
;             PG8_BAR; PG8_WAIT_L(0); PG8_MMA(1, 0, At, B0); PG8_BAR; PG8_SCHED;
;             PG8_STAGE(PG8_SB(1, 1), b3 + hstepB, voffB);
;             PG8_WAIT_V(6); PG8_BAR; PG8_MMA(1, 1, At, B1); PG8_BAR;
	s_waitcnt lgkmcnt(0)
	v_mfma_f32_16x16x32_bf16 v[60:63], v[132:135], v[148:151], v[60:63]
	v_mfma_f32_16x16x32_bf16 v[56:59], v[140:143], v[148:151], v[56:59]
	v_mfma_f32_16x16x32_bf16 v[44:47], v[132:135], v[156:159], v[44:47]
	v_mfma_f32_16x16x32_bf16 v[40:43], v[140:143], v[156:159], v[40:43]
	v_mfma_f32_16x16x32_bf16 v[28:31], v[132:135], v[164:167], v[28:31]
	v_mfma_f32_16x16x32_bf16 v[24:27], v[140:143], v[164:167], v[24:27]
	v_mfma_f32_16x16x32_bf16 v[12:15], v[132:135], v[172:175], v[12:15]
	v_mfma_f32_16x16x32_bf16 v[8:11], v[140:143], v[172:175], v[8:11]
	v_mfma_f32_16x16x32_bf16 v[60:63], v[136:139], v[152:155], v[60:63]
	v_mfma_f32_16x16x32_bf16 v[56:59], v[144:147], v[152:155], v[56:59]
	v_mfma_f32_16x16x32_bf16 v[44:47], v[136:139], v[160:163], v[44:47]
	v_mfma_f32_16x16x32_bf16 v[40:43], v[144:147], v[160:163], v[40:43]
	v_mfma_f32_16x16x32_bf16 v[28:31], v[136:139], v[168:171], v[28:31]
	v_mfma_f32_16x16x32_bf16 v[24:27], v[144:147], v[168:171], v[24:27]
	v_mfma_f32_16x16x32_bf16 v[12:15], v[136:139], v[198:201], v[12:15]
	v_mfma_f32_16x16x32_bf16 v[8:11], v[144:147], v[198:201], v[8:11]
	v_mfma_f32_16x16x32_bf16 v[52:55], v[214:217], v[148:151], v[52:55]
	v_mfma_f32_16x16x32_bf16 v[48:51], v[222:225], v[148:151], v[48:51]
	v_mfma_f32_16x16x32_bf16 v[36:39], v[214:217], v[156:159], v[36:39]
	v_mfma_f32_16x16x32_bf16 v[32:35], v[222:225], v[156:159], v[32:35]
	v_mfma_f32_16x16x32_bf16 v[20:23], v[214:217], v[164:167], v[20:23]
	v_mfma_f32_16x16x32_bf16 v[16:19], v[222:225], v[164:167], v[16:19]
	v_mfma_f32_16x16x32_bf16 v[4:7], v[214:217], v[172:175], v[4:7]
	v_mfma_f32_16x16x32_bf16 v[0:3], v[222:225], v[172:175], v[0:3]
	v_mfma_f32_16x16x32_bf16 v[52:55], v[218:221], v[152:155], v[52:55]
	v_mfma_f32_16x16x32_bf16 v[48:51], v[226:229], v[152:155], v[48:51]
	v_mfma_f32_16x16x32_bf16 v[36:39], v[218:221], v[160:163], v[36:39]
	v_mfma_f32_16x16x32_bf16 v[32:35], v[226:229], v[160:163], v[32:35]
	v_mfma_f32_16x16x32_bf16 v[20:23], v[218:221], v[168:171], v[20:23]
	v_mfma_f32_16x16x32_bf16 v[16:19], v[226:229], v[168:171], v[16:19]
	v_mfma_f32_16x16x32_bf16 v[4:7], v[218:221], v[198:201], v[4:7]
	v_mfma_f32_16x16x32_bf16 v[0:3], v[226:229], v[198:201], v[0:3]
	s_setprio 0
	s_barrier
	v_add_u32_e32 v144, 0x18000, v208
	v_add_u32_e32 v184, 0x1c000, v208
	ds_read_b128 v[132:135], v144
	ds_read_b128 v[136:139], v144 offset:1024
	ds_read_b128 v[140:143], v144 offset:2048
	ds_read_b128 v[144:147], v144 offset:3072
	ds_read_b128 v[214:217], v184
	ds_read_b128 v[218:221], v184 offset:1024
	ds_read_b128 v[222:225], v184 offset:2048
	ds_read_b128 v[226:229], v184 offset:3072
	s_mov_b32 m0, s69
	ds_read_b128 v[148:151], v211 offset:32768
	ds_read_b128 v[152:155], v211 offset:33792
	ds_read_b128 v[156:159], v211 offset:34816
	ds_read_b128 v[160:163], v211 offset:35840
	ds_read_b128 v[164:167], v211 offset:36864
	ds_read_b128 v[168:171], v211 offset:37888
	ds_read_b128 v[172:175], v211 offset:38912
	ds_read_b128 v[198:201], v211 offset:39936
	global_load_lds_dwordx4 v[234:235], off
	s_mov_b32 m0, s70
	v_lshl_add_u64 v[236:237], s[58:59], 0, v[178:179]
	global_load_lds_dwordx4 v[236:237], off
	s_add_i32 m0, s64, 0x16000
	s_nop 0
	global_load_lds_dwordx4 v[242:243], off
	s_waitcnt vmcnt(3)
	s_waitcnt lgkmcnt(8)
	s_setprio 1
	s_barrier
	s_waitcnt lgkmcnt(0)
	v_mfma_f32_16x16x32_bf16 v[124:127], v[132:135], v[148:151], v[124:127]
	v_mfma_f32_16x16x32_bf16 v[120:123], v[140:143], v[148:151], v[120:123]
	v_mfma_f32_16x16x32_bf16 v[108:111], v[132:135], v[156:159], v[108:111]
	v_mfma_f32_16x16x32_bf16 v[104:107], v[140:143], v[156:159], v[104:107]
	v_mfma_f32_16x16x32_bf16 v[92:95], v[132:135], v[164:167], v[92:95]
	v_mfma_f32_16x16x32_bf16 v[88:91], v[140:143], v[164:167], v[88:91]
	v_mfma_f32_16x16x32_bf16 v[76:79], v[132:135], v[172:175], v[76:79]
	v_mfma_f32_16x16x32_bf16 v[72:75], v[140:143], v[172:175], v[72:75]
	v_mfma_f32_16x16x32_bf16 v[124:127], v[136:139], v[152:155], v[124:127]
	v_mfma_f32_16x16x32_bf16 v[120:123], v[144:147], v[152:155], v[120:123]
	v_mfma_f32_16x16x32_bf16 v[108:111], v[136:139], v[160:163], v[108:111]
	v_mfma_f32_16x16x32_bf16 v[104:107], v[144:147], v[160:163], v[104:107]
	v_mfma_f32_16x16x32_bf16 v[92:95], v[136:139], v[168:171], v[92:95]
	v_mfma_f32_16x16x32_bf16 v[88:91], v[144:147], v[168:171], v[88:91]
	v_mfma_f32_16x16x32_bf16 v[76:79], v[136:139], v[198:201], v[76:79]
	v_mfma_f32_16x16x32_bf16 v[72:75], v[144:147], v[198:201], v[72:75]
	v_mfma_f32_16x16x32_bf16 v[116:119], v[214:217], v[148:151], v[116:119]
	v_mfma_f32_16x16x32_bf16 v[112:115], v[222:225], v[148:151], v[112:115]
	v_mfma_f32_16x16x32_bf16 v[100:103], v[214:217], v[156:159], v[100:103]
	v_mfma_f32_16x16x32_bf16 v[96:99], v[222:225], v[156:159], v[96:99]
	v_mfma_f32_16x16x32_bf16 v[84:87], v[214:217], v[164:167], v[84:87]
	v_mfma_f32_16x16x32_bf16 v[80:83], v[222:225], v[164:167], v[80:83]
	v_mfma_f32_16x16x32_bf16 v[68:71], v[214:217], v[172:175], v[68:71]
	v_mfma_f32_16x16x32_bf16 v[64:67], v[222:225], v[172:175], v[64:67]
	v_mfma_f32_16x16x32_bf16 v[116:119], v[218:221], v[152:155], v[116:119]
	v_mfma_f32_16x16x32_bf16 v[112:115], v[226:229], v[152:155], v[112:115]
	v_mfma_f32_16x16x32_bf16 v[100:103], v[218:221], v[160:163], v[100:103]
	v_mfma_f32_16x16x32_bf16 v[96:99], v[226:229], v[160:163], v[96:99]
	v_mfma_f32_16x16x32_bf16 v[84:87], v[218:221], v[168:171], v[84:87]
	v_mfma_f32_16x16x32_bf16 v[80:83], v[226:229], v[168:171], v[80:83]
	v_mfma_f32_16x16x32_bf16 v[68:71], v[218:221], v[198:201], v[68:71]
	v_mfma_f32_16x16x32_bf16 v[64:67], v[226:229], v[198:201], v[64:67]
	s_setprio 0
	s_barrier
; #define PG8_STAGE(bufoff, gbase, voff) do { _Pragma("unroll") for (int _i = 0; _i < 2; ++_i) \
;         __builtin_amdgcn_global_load_lds((const unsigned*)((const char*)(gbase) + (voff)[_i]), (LAS unsigned*)(lds + (bufoff) + ldsw + _i * 8192), 16, 0, 0); } while (0)
; #define PG8_LDA(dst, b, h) do { _Pragma("unroll") for (int m = 0; m < 4; ++m) _Pragma("unroll") for (int k = 0; k < 2; ++k) dst[m][k] = *(const LAS bf16x8*)(lds + PG8_SA(b, h) + aoff + m * 2048 + k * 1024); } while (0)
; #define PG8_LDB(dst, b, h) do { _Pragma("unroll") for (int n = 0; n < 2; ++n) _Pragma("unroll") for (int k = 0; k < 2; ++k) dst[n][k] = *(const LAS bf16x8*)(lds + PG8_SB(b, h) + boff + n * 2048 + k * 1024); } while (0)
; #define PG8_WAIT_V(n) asm volatile("s_waitcnt vmcnt(" #n ")" ::: "memory")
; #define PG8_WAIT_L(n) asm volatile("s_waitcnt lgkmcnt(" #n ")" ::: "memory")
; #define PG8_BAR __builtin_amdgcn_s_barrier()
; #define PG8_SCHED __builtin_amdgcn_sched_barrier(0)
; template <class Epi>
; DI void gemm_phase(LAS unsigned char* lds, const Gemm g, const StaticOrder& S_, const Epi& E) {
;     ...
;             PG8_LDB(B0, 1, 0); PG8_SCHED; PG8_LDA(At, 1, 0); PG8_STAGE(PG8_SA(0, 1), a2 + hstepA, voffA);
;             PG8_WAIT_L(8); PG8_BAR; PG8_WAIT_L(0); PG8_MMA(0, 0, At, B0); PG8_BAR; PG8_SCHED;
;             PG8_LDB(B1, 1, 1); PG8_STAGE(PG8_SB(1, 0), b3, voffB);
;             PG8_BAR; PG8_WAIT_L(0); PG8_MMA(0, 1, At, B1); PG8_BAR;
;             PG8_LDA(At, 1, 1); PG8_STAGE(PG8_SA(1, 0), a3, voffA);
;             PG8_BAR; PG8_WAIT_L(0); PG8_MMA(1, 0, At, B0); PG8_BAR; PG8_SCHED;
;             PG8_STAGE(PG8_SB(1, 1), b3 + hstepB, voffB);
;             PG8_WAIT_V(6); PG8_BAR; PG8_MMA(1, 1, At, B1); PG8_BAR;
;     DI void operator()(const f32x4 (&acc)[2][2][4][2], const pg8::Unit& u, int wr, int wc, int fr, int fq) const {
;         const int pn = u.pn; bf16_t* base; int ld, colt;
;         if (pn < 8) { base = (bf16_t*)(ws + WS_ZU) + (size_t)pn * S * 256; ld = 256; colt = 0; }
;         else if (pn < 16) { base = (bf16_t*)(ws + WS_ZG); ld = 2048; colt = (pn - 8) * 256; }
;         else if (pn < 28) { base = (bf16_t*)(ws + WS_ZQKV); ld = 3072; colt = (pn - 16) * 256; }
;         else if (pn < 36) { base = (bf16_t*)(ws + WS_ZGA); ld = 2048; colt = (pn - 28) * 256; }
;         else { base = (bf16_t*)(ws + WS_ZM) + (size_t)(pn - 36) * S * 256; ld = 256; colt = 0; }
	ds_read_b128 v[148:151], v211 offset:49152
	ds_read_b128 v[152:155], v211 offset:50176
	ds_read_b128 v[156:159], v211 offset:51200
	ds_read_b128 v[160:163], v211 offset:52224
	ds_read_b128 v[164:167], v211 offset:53248
	ds_read_b128 v[168:171], v211 offset:54272
	ds_read_b128 v[172:175], v211 offset:55296
	ds_read_b128 v[198:201], v211 offset:56320
	s_add_i32 m0, s64, 0x18000
	v_lshl_add_u64 v[230:231], v[230:231], 0, s[22:23]
	global_load_lds_dwordx4 v[230:231], off
	s_add_i32 m0, s64, 0x1a000
	v_lshl_add_u64 v[230:231], v[232:233], 0, s[22:23]
	global_load_lds_dwordx4 v[230:231], off
	s_add_u32 s56, s56, 0x80080
	s_addc_u32 s57, s57, 0
	s_add_i32 m0, s64, 0x1c000
	v_lshl_add_u64 v[238:239], s[56:57], 0, v[180:181]
	global_load_lds_dwordx4 v[238:239], off
	v_lshl_add_u64 v[250:251], s[56:57], 0, v[176:177]
	s_add_u32 s58, s58, 0x80000
	s_addc_u32 s59, s59, 0
	s_mov_b32 m0, s71
	v_lshl_add_u64 v[240:241], s[58:59], 0, v[182:183]
	global_load_lds_dwordx4 v[240:241], off
	s_mov_b32 m0, s72
	v_lshl_add_u64 v[240:241], s[58:59], 0, v[178:179]
	global_load_lds_dwordx4 v[240:241], off
	s_waitcnt vmcnt(5)
	s_setprio 1
	s_barrier
	s_waitcnt lgkmcnt(0)
	v_mfma_f32_16x16x32_bf16 v[60:63], v[132:135], v[148:151], v[60:63]
	v_mfma_f32_16x16x32_bf16 v[56:59], v[140:143], v[148:151], v[56:59]
	v_mfma_f32_16x16x32_bf16 v[44:47], v[132:135], v[156:159], v[44:47]
	v_mfma_f32_16x16x32_bf16 v[40:43], v[140:143], v[156:159], v[40:43]
	v_mfma_f32_16x16x32_bf16 v[28:31], v[132:135], v[164:167], v[28:31]
	v_mfma_f32_16x16x32_bf16 v[24:27], v[140:143], v[164:167], v[24:27]
	v_mfma_f32_16x16x32_bf16 v[12:15], v[132:135], v[172:175], v[12:15]
	v_mfma_f32_16x16x32_bf16 v[8:11], v[140:143], v[172:175], v[8:11]
	v_mfma_f32_16x16x32_bf16 v[60:63], v[136:139], v[152:155], v[60:63]
	v_mfma_f32_16x16x32_bf16 v[56:59], v[144:147], v[152:155], v[56:59]
	v_mfma_f32_16x16x32_bf16 v[44:47], v[136:139], v[160:163], v[44:47]
	v_mfma_f32_16x16x32_bf16 v[40:43], v[144:147], v[160:163], v[40:43]
	v_mfma_f32_16x16x32_bf16 v[28:31], v[136:139], v[168:171], v[28:31]
	v_mfma_f32_16x16x32_bf16 v[24:27], v[144:147], v[168:171], v[24:27]
	v_mfma_f32_16x16x32_bf16 v[12:15], v[136:139], v[198:201], v[12:15]
	v_mfma_f32_16x16x32_bf16 v[8:11], v[144:147], v[198:201], v[8:11]
	v_mfma_f32_16x16x32_bf16 v[52:55], v[214:217], v[148:151], v[52:55]
	v_mfma_f32_16x16x32_bf16 v[48:51], v[222:225], v[148:151], v[48:51]
	v_mfma_f32_16x16x32_bf16 v[36:39], v[214:217], v[156:159], v[36:39]
	v_mfma_f32_16x16x32_bf16 v[32:35], v[222:225], v[156:159], v[32:35]
	v_mfma_f32_16x16x32_bf16 v[20:23], v[214:217], v[164:167], v[20:23]
	v_mfma_f32_16x16x32_bf16 v[16:19], v[222:225], v[164:167], v[16:19]
	v_mfma_f32_16x16x32_bf16 v[4:7], v[214:217], v[172:175], v[4:7]
	v_mfma_f32_16x16x32_bf16 v[0:3], v[222:225], v[172:175], v[0:3]
	v_mfma_f32_16x16x32_bf16 v[52:55], v[218:221], v[152:155], v[52:55]
	v_mfma_f32_16x16x32_bf16 v[48:51], v[226:229], v[152:155], v[48:51]
	v_mfma_f32_16x16x32_bf16 v[36:39], v[218:221], v[160:163], v[36:39]
	v_mfma_f32_16x16x32_bf16 v[32:35], v[226:229], v[160:163], v[32:35]
	v_mfma_f32_16x16x32_bf16 v[20:23], v[218:221], v[168:171], v[20:23]
	v_mfma_f32_16x16x32_bf16 v[16:19], v[226:229], v[168:171], v[16:19]
	v_mfma_f32_16x16x32_bf16 v[4:7], v[218:221], v[198:201], v[4:7]
	v_mfma_f32_16x16x32_bf16 v[0:3], v[226:229], v[198:201], v[0:3]
	s_setprio 0
	s_add_u32 s54, s54, 0x100
	s_addc_u32 s55, s55, 0
	s_mov_b32 s56, s94
	s_barrier
	s_cbranch_vccz .LBB0_114
	s_cmp_gt_i32 s50, 7
	s_mov_b64 s[54:55], -1
	s_cbranch_scc0 .LBB0_128
	s_cmp_gt_u32 s50, 15
	s_cbranch_scc0 .LBB0_125
	s_cmp_gt_u32 s50, 27
	s_cbranch_scc0 .LBB0_122
	s_cmp_gt_u32 s50, 35
	s_mov_b64 s[48:49], -1
	s_cbranch_scc0 .LBB0_120
	s_sub_i32 s18, s50, 36
	s_lshl_b64 s[6:7], s[18:19], 23
	s_add_u32 s6, s78, s6
	s_addc_u32 s7, s79, s7
	s_mov_b64 s[48:49], 0
